# GEMM staging: odd LDS subtiles rotated by 64 B so ds_write_b128 lane groups no longer hit the same banks twice
# speedup vs baseline: 1.0431x; 1.0088x over previous
.LBB0_193:
	s_ashr_i32 s13, s12, 31
	s_ashr_i32 s45, s44, 31
	s_lshl_b64 s[8:9], s[12:13], 18
	s_lshl_b64 s[10:11], s[44:45], 18
	s_add_u32 s20, s6, s8
	v_mov_b32_e32 v13, v197
	s_addc_u32 s21, s7, s9
	s_add_u32 s34, s14, s10
	v_ashrrev_i32_e32 v9, 3, v13
	v_and_b32_e32 v16, 7, v13
	v_lshlrev_b32_e32 v84, 3, v16
	v_lshlrev_b32_e32 v16, 6, v9
	s_addc_u32 s35, s15, s11
	v_readlane_b32 s3, v248, 0
	v_and_b32_e32 v16, 0x3c0, v16
	v_lshlrev_b32_e32 v85, 4, v13
	s_cmp_lg_u32 s19, s3
	v_lshrrev_b32_e32 v17, 6, v13
	v_bfe_u32 v86, v13, 2, 1
	v_and_or_b32 v87, v85, 48, v16
	v_lshlrev_b32_e32 v16, 2, v9
	v_lshlrev_b32_e32 v85, 10, v9
	s_mov_b32 s3, 0x3ffffe
	v_and_b32_e32 v88, 32, v16
	v_or_b32_e32 v16, v85, v84
	v_and_or_b32 v9, v17, s3, v86
	v_mov_b32_e32 v17, v2
	v_lshlrev_b32_e32 v9, 10, v9
	v_lshlrev_b64 v[148:149], 1, v[16:17]
	v_bitop3_b32 v9, v87, v9, v88 bitop3:0xde
	v_and_b32_e32 v253, 4, v197
	v_lshlrev_b32_e32 v253, 4, v253
	v_add_u32_e32 v253, v253, v9
	v_and_b32_e32 v253, 0x3ff, v253
	v_and_b32_e32 v9, 0xfffffc00, v9
	v_or_b32_e32 v9, v9, v253
	v_lshl_add_u64 v[152:153], s[20:21], 0, v[148:149]
	v_lshl_add_u64 v[150:151], s[34:35], 0, v[148:149]
	s_cbranch_scc1 .LBB0_195
	v_add_co_u32_e32 v86, vcc, 0x10000, v152
	global_load_dwordx4 v[52:55], v[152:153], off
	global_load_dwordx4 v[56:59], v[150:151], off
	v_addc_co_u32_e32 v87, vcc, 0, v153, vcc
	v_add_co_u32_e32 v88, vcc, 0x10000, v150
	global_load_dwordx4 v[60:63], v[86:87], off
	s_nop 0
	v_addc_co_u32_e32 v89, vcc, 0, v151, vcc
	v_add_co_u32_e32 v90, vcc, 0x20000, v152
	global_load_dwordx4 v[64:67], v[88:89], off
	s_nop 0
	v_addc_co_u32_e32 v91, vcc, 0, v153, vcc
	v_add_co_u32_e32 v92, vcc, 0x20000, v150
	global_load_dwordx4 v[68:71], v[90:91], off
	s_nop 0
	v_addc_co_u32_e32 v93, vcc, 0, v151, vcc
	v_add_co_u32_e32 v94, vcc, 0x30000, v152
	global_load_dwordx4 v[72:75], v[92:93], off
	s_nop 0
	v_addc_co_u32_e32 v95, vcc, 0, v153, vcc
	global_load_dwordx4 v[76:79], v[94:95], off
	v_add_co_u32_e32 v96, vcc, 0x30000, v150
	s_nop 1
	v_addc_co_u32_e32 v97, vcc, 0, v151, vcc
	global_load_dwordx4 v[80:83], v[96:97], off
	global_load_dwordx4 v[20:23], v[152:153], off offset:128
	global_load_dwordx4 v[24:27], v[150:151], off offset:128
	global_load_dwordx4 v[28:31], v[86:87], off offset:128
	global_load_dwordx4 v[36:39], v[88:89], off offset:128
	global_load_dwordx4 v[32:35], v[90:91], off offset:128
	global_load_dwordx4 v[44:47], v[92:93], off offset:128
	global_load_dwordx4 v[40:43], v[94:95], off offset:128
	global_load_dwordx4 v[48:51], v[96:97], off offset:128
	s_barrier
	s_waitcnt vmcnt(15)
	ds_write_b128 v9, v[52:55]
	s_waitcnt vmcnt(14)
	ds_write_b128 v9, v[56:59] offset:16384
	s_waitcnt vmcnt(13)
	ds_write_b128 v9, v[60:63] offset:4096
	s_waitcnt vmcnt(12)
	ds_write_b128 v9, v[64:67] offset:20480
	s_waitcnt vmcnt(11)
	ds_write_b128 v9, v[68:71] offset:8192
	s_waitcnt vmcnt(10)
	ds_write_b128 v9, v[72:75] offset:24576
	s_waitcnt vmcnt(9)
	ds_write_b128 v9, v[76:79] offset:12288
	s_waitcnt vmcnt(8)
	ds_write_b128 v9, v[80:83] offset:28672
	global_load_dwordx4 v[52:55], v[152:153], off offset:256
	global_load_dwordx4 v[56:59], v[150:151], off offset:256
	global_load_dwordx4 v[60:63], v[86:87], off offset:256
	global_load_dwordx4 v[68:71], v[88:89], off offset:256
	global_load_dwordx4 v[64:67], v[90:91], off offset:256
	global_load_dwordx4 v[76:79], v[92:93], off offset:256
	global_load_dwordx4 v[72:75], v[94:95], off offset:256
	global_load_dwordx4 v[80:83], v[96:97], off offset:256
.LBB0_195:
	s_add_u32 s10, s16, s10
	s_addc_u32 s11, s17, s11
	v_lshlrev_b32_e32 v86, 6, v13
	v_lshlrev_b32_e32 v88, 2, v13
	v_add_u32_e32 v84, v85, v84
	v_mov_b32_e32 v85, v2
	s_add_u32 s8, s24, s8
	v_and_b32_e32 v87, 0x3c0, v86
	v_and_b32_e32 v88, 32, v88
	v_and_b32_e32 v89, 48, v13
	v_lshlrev_b32_e32 v13, 7, v13
	v_lshlrev_b64 v[84:85], 1, v[84:85]
	s_addc_u32 s9, s25, s9
	v_bitop3_b32 v87, v87, v88, v89 bitop3:0x36
	v_and_b32_e32 v86, 0xffffe000, v86
	v_and_b32_e32 v88, 0x2000, v13
	v_lshl_add_u64 v[154:155], s[10:11], 0, v[84:85]
	v_lshl_add_u64 v[156:157], s[8:9], 0, v[84:85]
	v_mov_b32_e32 v84, 0
	s_mov_b64 s[8:9], 0
	v_add_u32_e32 v13, v87, v86
	v_add_u32_e32 v231, v87, v88
	v_add_u32_e32 v253, 64, v13
	v_and_b32_e32 v253, 0x3ff, v253
	v_and_b32_e32 v251, 0xfffffc00, v13
	v_or_b32_e32 v251, v251, v253
	v_add_u32_e32 v253, 64, v231
	v_and_b32_e32 v253, 0x3ff, v253
	v_and_b32_e32 v252, 0xfffffc00, v231
	v_or_b32_e32 v252, v252, v253
	v_mov_b32_e32 v85, v84
	v_mov_b32_e32 v86, v84
	v_mov_b32_e32 v87, v84
	v_mov_b32_e32 v88, v84
	v_mov_b32_e32 v89, v84
	v_mov_b32_e32 v90, v84
	v_mov_b32_e32 v91, v84
	v_mov_b32_e32 v92, v84
	v_mov_b32_e32 v93, v84
	v_mov_b32_e32 v94, v84
	v_mov_b32_e32 v95, v84
	v_mov_b32_e32 v96, v84
	v_mov_b32_e32 v97, v84
	v_mov_b32_e32 v98, v84
	v_mov_b32_e32 v99, v84
	v_mov_b32_e32 v100, v84
	v_mov_b32_e32 v101, v84
	v_mov_b32_e32 v102, v84
	v_mov_b32_e32 v103, v84
	v_mov_b32_e32 v104, v84
	v_mov_b32_e32 v105, v84
	v_mov_b32_e32 v106, v84
	v_mov_b32_e32 v107, v84
	v_mov_b32_e32 v108, v84
	v_mov_b32_e32 v109, v84
	v_mov_b32_e32 v110, v84
	v_mov_b32_e32 v111, v84
	v_mov_b32_e32 v112, v84
	v_mov_b32_e32 v113, v84
	v_mov_b32_e32 v114, v84
	v_mov_b32_e32 v115, v84
	v_mov_b32_e32 v116, v84
	v_mov_b32_e32 v117, v84
	v_mov_b32_e32 v118, v84
	v_mov_b32_e32 v119, v84
	v_mov_b32_e32 v120, v84
	v_mov_b32_e32 v121, v84
	v_mov_b32_e32 v122, v84
	v_mov_b32_e32 v123, v84
	v_mov_b32_e32 v124, v84
	v_mov_b32_e32 v125, v84
	v_mov_b32_e32 v126, v84
	v_mov_b32_e32 v127, v84
	v_mov_b32_e32 v128, v84
	v_mov_b32_e32 v129, v84
	v_mov_b32_e32 v130, v84
	v_mov_b32_e32 v131, v84
	v_mov_b32_e32 v132, v84
	v_mov_b32_e32 v133, v84
	v_mov_b32_e32 v134, v84
	v_mov_b32_e32 v135, v84
	v_mov_b32_e32 v136, v84
	v_mov_b32_e32 v137, v84
	v_mov_b32_e32 v138, v84
	v_mov_b32_e32 v139, v84
	v_mov_b32_e32 v140, v84
	v_mov_b32_e32 v141, v84
	v_mov_b32_e32 v142, v84
	v_mov_b32_e32 v143, v84
	v_mov_b32_e32 v144, v84
	v_mov_b32_e32 v145, v84
	v_mov_b32_e32 v146, v84
	v_mov_b32_e32 v147, v84
	s_waitcnt lgkmcnt(0)
	s_barrier
.LBB0_196:
	v_lshl_add_u64 v[232:233], v[156:157], 0, s[8:9]
	v_lshl_add_u64 v[234:235], v[154:155], 0, s[8:9]
	s_setprio 1
	ds_read_b128 v[158:161], v231 offset:16384
	ds_read_b128 v[162:165], v231 offset:18432
	ds_read_b128 v[166:169], v13
	ds_read_b128 v[170:173], v13 offset:2048
	ds_read_b128 v[174:177], v231 offset:20480
	ds_read_b128 v[178:181], v231 offset:22528
	ds_read_b128 v[182:185], v13 offset:4096
	ds_read_b128 v[186:189], v13 offset:6144
	s_waitcnt lgkmcnt(5)
	v_mfma_f32_16x16x32_bf16 v[144:147], v[158:161], v[166:169], v[144:147]
	v_mfma_f32_16x16x32_bf16 v[140:143], v[162:165], v[166:169], v[140:143]
	s_waitcnt lgkmcnt(3)
	v_mfma_f32_16x16x32_bf16 v[136:139], v[174:177], v[166:169], v[136:139]
	s_waitcnt lgkmcnt(2)
	v_mfma_f32_16x16x32_bf16 v[132:135], v[178:181], v[166:169], v[132:135]
	v_add_co_u32_e32 v236, vcc, s27, v232
	s_waitcnt vmcnt(15)
	ds_write_b128 v9, v[20:23] offset:32768
	v_addc_co_u32_e32 v237, vcc, 0, v233, vcc
	global_load_dwordx4 v[20:23], v[236:237], off offset:384
	v_mfma_f32_16x16x32_bf16 v[128:131], v[158:161], v[170:173], v[128:131]
	v_mfma_f32_16x16x32_bf16 v[124:127], v[162:165], v[170:173], v[124:127]
	v_mfma_f32_16x16x32_bf16 v[120:123], v[174:177], v[170:173], v[120:123]
	v_mfma_f32_16x16x32_bf16 v[116:119], v[178:181], v[170:173], v[116:119]
	v_add_co_u32_e32 v238, vcc, s33, v234
	s_waitcnt vmcnt(15)
	ds_write_b128 v9, v[24:27] offset:49152
	v_addc_co_u32_e32 v239, vcc, 0, v235, vcc
	global_load_dwordx4 v[24:27], v[238:239], off offset:384
	s_waitcnt lgkmcnt(3)
	v_mfma_f32_16x16x32_bf16 v[112:115], v[158:161], v[182:185], v[112:115]
	v_mfma_f32_16x16x32_bf16 v[108:111], v[162:165], v[182:185], v[108:111]
	v_mfma_f32_16x16x32_bf16 v[104:107], v[174:177], v[182:185], v[104:107]
	v_mfma_f32_16x16x32_bf16 v[100:103], v[178:181], v[182:185], v[100:103]
	v_add_co_u32_e32 v240, vcc, s30, v232
	s_waitcnt vmcnt(15)
	ds_write_b128 v9, v[28:31] offset:36864
	v_addc_co_u32_e32 v241, vcc, 0, v233, vcc
	global_load_dwordx4 v[28:31], v[240:241], off offset:384
	s_waitcnt lgkmcnt(3)
	v_mfma_f32_16x16x32_bf16 v[96:99], v[158:161], v[186:189], v[96:99]
	v_mfma_f32_16x16x32_bf16 v[92:95], v[162:165], v[186:189], v[92:95]
	v_mfma_f32_16x16x32_bf16 v[88:91], v[174:177], v[186:189], v[88:91]
	v_mfma_f32_16x16x32_bf16 v[84:87], v[178:181], v[186:189], v[84:87]
	s_mov_b32 s3, 0x18000
	v_add_co_u32_e32 v242, vcc, s3, v234
	s_waitcnt vmcnt(15)
	ds_write_b128 v9, v[36:39] offset:53248
	v_addc_co_u32_e32 v243, vcc, 0, v235, vcc
	global_load_dwordx4 v[36:39], v[242:243], off offset:384
	ds_read_b128 v[158:161], v252 offset:17408
	ds_read_b128 v[162:165], v252 offset:19456
	ds_read_b128 v[166:169], v251 offset:1024
	ds_read_b128 v[170:173], v251 offset:3072
	ds_read_b128 v[174:177], v252 offset:21504
	ds_read_b128 v[178:181], v252 offset:23552
	ds_read_b128 v[182:185], v251 offset:5120
	ds_read_b128 v[186:189], v251 offset:7168
	s_waitcnt lgkmcnt(5)
	v_mfma_f32_16x16x32_bf16 v[144:147], v[158:161], v[166:169], v[144:147]
	v_mfma_f32_16x16x32_bf16 v[140:143], v[162:165], v[166:169], v[140:143]
	s_waitcnt lgkmcnt(3)
	v_mfma_f32_16x16x32_bf16 v[136:139], v[174:177], v[166:169], v[136:139]
	s_waitcnt lgkmcnt(2)
	v_mfma_f32_16x16x32_bf16 v[132:135], v[178:181], v[166:169], v[132:135]
	v_add_co_u32_e32 v244, vcc, s31, v232
	s_waitcnt vmcnt(15)
	ds_write_b128 v9, v[32:35] offset:40960
	v_addc_co_u32_e32 v245, vcc, 0, v233, vcc
	global_load_dwordx4 v[32:35], v[244:245], off offset:384
	v_mfma_f32_16x16x32_bf16 v[128:131], v[158:161], v[170:173], v[128:131]
	v_mfma_f32_16x16x32_bf16 v[124:127], v[162:165], v[170:173], v[124:127]
	v_mfma_f32_16x16x32_bf16 v[120:123], v[174:177], v[170:173], v[120:123]
	v_mfma_f32_16x16x32_bf16 v[116:119], v[178:181], v[170:173], v[116:119]
	s_mov_b32 s3, 0x28000
	v_add_co_u32_e32 v246, vcc, s3, v234
	s_waitcnt vmcnt(15)
	ds_write_b128 v9, v[44:47] offset:57344
	v_addc_co_u32_e32 v247, vcc, 0, v235, vcc
	global_load_dwordx4 v[44:47], v[246:247], off offset:384
	s_waitcnt lgkmcnt(3)
	v_mfma_f32_16x16x32_bf16 v[112:115], v[158:161], v[182:185], v[112:115]
	v_mfma_f32_16x16x32_bf16 v[108:111], v[162:165], v[182:185], v[108:111]
	v_mfma_f32_16x16x32_bf16 v[104:107], v[174:177], v[182:185], v[104:107]
	v_mfma_f32_16x16x32_bf16 v[100:103], v[178:181], v[182:185], v[100:103]
	v_add_co_u32_e32 v232, vcc, s92, v232
	s_waitcnt vmcnt(15)
	ds_write_b128 v9, v[40:43] offset:45056
	v_addc_co_u32_e32 v233, vcc, 0, v233, vcc
	global_load_dwordx4 v[40:43], v[232:233], off offset:384
	s_waitcnt lgkmcnt(3)
	v_mfma_f32_16x16x32_bf16 v[96:99], v[158:161], v[186:189], v[96:99]
	v_mfma_f32_16x16x32_bf16 v[92:95], v[162:165], v[186:189], v[92:95]
	v_mfma_f32_16x16x32_bf16 v[88:91], v[174:177], v[186:189], v[88:91]
	v_mfma_f32_16x16x32_bf16 v[84:87], v[178:181], v[186:189], v[84:87]
	s_mov_b32 s3, 0x38000
	v_add_co_u32_e32 v234, vcc, s3, v234
	s_waitcnt vmcnt(7)
	ds_write_b128 v9, v[48:51] offset:61440
	v_addc_co_u32_e32 v235, vcc, 0, v235, vcc
	global_load_dwordx4 v[48:51], v[234:235], off offset:384
	s_setprio 0
	s_waitcnt lgkmcnt(0)
	s_barrier
	s_setprio 1
	ds_read_b128 v[158:161], v231 offset:49152
	ds_read_b128 v[162:165], v231 offset:51200
	ds_read_b128 v[166:169], v13 offset:32768
	ds_read_b128 v[170:173], v13 offset:34816
	ds_read_b128 v[174:177], v231 offset:53248
	ds_read_b128 v[178:181], v231 offset:55296
	ds_read_b128 v[182:185], v13 offset:36864
	ds_read_b128 v[186:189], v13 offset:38912
	s_waitcnt lgkmcnt(5)
	v_mfma_f32_16x16x32_bf16 v[144:147], v[158:161], v[166:169], v[144:147]
	v_mfma_f32_16x16x32_bf16 v[140:143], v[162:165], v[166:169], v[140:143]
	s_waitcnt lgkmcnt(3)
	v_mfma_f32_16x16x32_bf16 v[136:139], v[174:177], v[166:169], v[136:139]
	s_waitcnt lgkmcnt(2)
	v_mfma_f32_16x16x32_bf16 v[132:135], v[178:181], v[166:169], v[132:135]
	s_waitcnt vmcnt(15)
	ds_write_b128 v9, v[52:55]
	global_load_dwordx4 v[52:55], v[236:237], off offset:512
	v_mfma_f32_16x16x32_bf16 v[128:131], v[158:161], v[170:173], v[128:131]
	v_mfma_f32_16x16x32_bf16 v[124:127], v[162:165], v[170:173], v[124:127]
	v_mfma_f32_16x16x32_bf16 v[120:123], v[174:177], v[170:173], v[120:123]
	v_mfma_f32_16x16x32_bf16 v[116:119], v[178:181], v[170:173], v[116:119]
	s_waitcnt vmcnt(15)
	ds_write_b128 v9, v[56:59] offset:16384
	global_load_dwordx4 v[56:59], v[238:239], off offset:512
	s_waitcnt lgkmcnt(3)
	v_mfma_f32_16x16x32_bf16 v[112:115], v[158:161], v[182:185], v[112:115]
	v_mfma_f32_16x16x32_bf16 v[108:111], v[162:165], v[182:185], v[108:111]
	v_mfma_f32_16x16x32_bf16 v[104:107], v[174:177], v[182:185], v[104:107]
	v_mfma_f32_16x16x32_bf16 v[100:103], v[178:181], v[182:185], v[100:103]
	s_waitcnt vmcnt(15)
	ds_write_b128 v9, v[60:63] offset:4096
	global_load_dwordx4 v[60:63], v[240:241], off offset:512
	s_waitcnt lgkmcnt(3)
	v_mfma_f32_16x16x32_bf16 v[96:99], v[158:161], v[186:189], v[96:99]
	v_mfma_f32_16x16x32_bf16 v[92:95], v[162:165], v[186:189], v[92:95]
	v_mfma_f32_16x16x32_bf16 v[88:91], v[174:177], v[186:189], v[88:91]
	v_mfma_f32_16x16x32_bf16 v[84:87], v[178:181], v[186:189], v[84:87]
	s_waitcnt vmcnt(15)
	ds_write_b128 v9, v[68:71] offset:20480
	global_load_dwordx4 v[68:71], v[242:243], off offset:512
	ds_read_b128 v[158:161], v252 offset:50176
	ds_read_b128 v[162:165], v252 offset:52224
	ds_read_b128 v[166:169], v251 offset:33792
	ds_read_b128 v[170:173], v251 offset:35840
	ds_read_b128 v[174:177], v252 offset:54272
	ds_read_b128 v[178:181], v252 offset:56320
	ds_read_b128 v[182:185], v251 offset:37888
	ds_read_b128 v[186:189], v251 offset:39936
	s_waitcnt lgkmcnt(5)
	v_mfma_f32_16x16x32_bf16 v[144:147], v[158:161], v[166:169], v[144:147]
	v_mfma_f32_16x16x32_bf16 v[140:143], v[162:165], v[166:169], v[140:143]
	s_waitcnt lgkmcnt(3)
	v_mfma_f32_16x16x32_bf16 v[136:139], v[174:177], v[166:169], v[136:139]
	s_waitcnt lgkmcnt(2)
	v_mfma_f32_16x16x32_bf16 v[132:135], v[178:181], v[166:169], v[132:135]
	s_waitcnt vmcnt(15)
	ds_write_b128 v9, v[64:67] offset:8192
	global_load_dwordx4 v[64:67], v[244:245], off offset:512
	v_mfma_f32_16x16x32_bf16 v[128:131], v[158:161], v[170:173], v[128:131]
	v_mfma_f32_16x16x32_bf16 v[124:127], v[162:165], v[170:173], v[124:127]
	v_mfma_f32_16x16x32_bf16 v[120:123], v[174:177], v[170:173], v[120:123]
	v_mfma_f32_16x16x32_bf16 v[116:119], v[178:181], v[170:173], v[116:119]
	s_waitcnt vmcnt(15)
	ds_write_b128 v9, v[76:79] offset:24576
	global_load_dwordx4 v[76:79], v[246:247], off offset:512
	s_waitcnt lgkmcnt(3)
	v_mfma_f32_16x16x32_bf16 v[112:115], v[158:161], v[182:185], v[112:115]
	v_mfma_f32_16x16x32_bf16 v[108:111], v[162:165], v[182:185], v[108:111]
	v_mfma_f32_16x16x32_bf16 v[104:107], v[174:177], v[182:185], v[104:107]
	v_mfma_f32_16x16x32_bf16 v[100:103], v[178:181], v[182:185], v[100:103]
	s_waitcnt vmcnt(15)
	ds_write_b128 v9, v[72:75] offset:12288
	global_load_dwordx4 v[72:75], v[232:233], off offset:512
	s_waitcnt lgkmcnt(3)
	v_mfma_f32_16x16x32_bf16 v[96:99], v[158:161], v[186:189], v[96:99]
	v_mfma_f32_16x16x32_bf16 v[92:95], v[162:165], v[186:189], v[92:95]
	v_mfma_f32_16x16x32_bf16 v[88:91], v[174:177], v[186:189], v[88:91]
	v_mfma_f32_16x16x32_bf16 v[84:87], v[178:181], v[186:189], v[84:87]
	s_waitcnt vmcnt(15)
	ds_write_b128 v9, v[80:83] offset:28672
	global_load_dwordx4 v[80:83], v[234:235], off offset:512
	s_setprio 0
	s_add_u32 s8, s8, 0x100
	s_addc_u32 s9, s9, 0
	s_cmpk_eq_i32 s8, 0x600
	s_waitcnt lgkmcnt(0)
	s_barrier
	s_cbranch_scc0 .LBB0_196
	s_ashr_i32 s3, s2, 31
	s_lshl_b64 s[2:3], s[2:3], 18
	s_add_u32 s2, s6, s2
	s_addc_u32 s3, s7, s3
	s_setprio 1
	ds_read_b128 v[154:157], v231 offset:16384
	ds_read_b128 v[158:161], v231 offset:18432
	ds_read_b128 v[162:165], v13
	ds_read_b128 v[166:169], v13 offset:2048
	ds_read_b128 v[170:173], v231 offset:20480
	ds_read_b128 v[174:177], v231 offset:22528
	ds_read_b128 v[178:181], v13 offset:4096
	ds_read_b128 v[182:185], v13 offset:6144
	s_waitcnt lgkmcnt(5)
	v_mfma_f32_16x16x32_bf16 v[144:147], v[154:157], v[162:165], v[144:147]
	v_mfma_f32_16x16x32_bf16 v[140:143], v[158:161], v[162:165], v[140:143]
	s_waitcnt lgkmcnt(3)
	v_mfma_f32_16x16x32_bf16 v[136:139], v[170:173], v[162:165], v[136:139]
	s_waitcnt lgkmcnt(2)
	v_mfma_f32_16x16x32_bf16 v[132:135], v[174:177], v[162:165], v[132:135]
	s_waitcnt vmcnt(15)
	ds_write_b128 v9, v[20:23] offset:32768
	global_load_dwordx4 v[20:23], v[152:153], off offset:1920
	v_mfma_f32_16x16x32_bf16 v[128:131], v[154:157], v[166:169], v[128:131]
	v_mfma_f32_16x16x32_bf16 v[124:127], v[158:161], v[166:169], v[124:127]
	v_mfma_f32_16x16x32_bf16 v[120:123], v[170:173], v[166:169], v[120:123]
	v_mfma_f32_16x16x32_bf16 v[116:119], v[174:177], v[166:169], v[116:119]
	s_waitcnt vmcnt(15)
	ds_write_b128 v9, v[24:27] offset:49152
	global_load_dwordx4 v[24:27], v[150:151], off offset:1920
	s_waitcnt lgkmcnt(3)
	v_mfma_f32_16x16x32_bf16 v[112:115], v[154:157], v[178:181], v[112:115]
	v_mfma_f32_16x16x32_bf16 v[108:111], v[158:161], v[178:181], v[108:111]
	v_mfma_f32_16x16x32_bf16 v[162:165], v[170:173], v[178:181], v[104:107]
	v_mfma_f32_16x16x32_bf16 v[166:169], v[174:177], v[178:181], v[100:103]
	s_mov_b32 s8, 0x10000
	s_waitcnt vmcnt(15)
	ds_write_b128 v9, v[28:31] offset:36864
	v_add_co_u32_e32 v28, vcc, s8, v152
	s_nop 1
	v_addc_co_u32_e32 v29, vcc, 0, v153, vcc
	global_load_dwordx4 v[28:31], v[28:29], off offset:1920
	s_waitcnt lgkmcnt(3)
	v_mfma_f32_16x16x32_bf16 v[96:99], v[154:157], v[182:185], v[96:99]
	v_mfma_f32_16x16x32_bf16 v[92:95], v[158:161], v[182:185], v[92:95]
	v_mfma_f32_16x16x32_bf16 v[88:91], v[170:173], v[182:185], v[88:91]
	v_mfma_f32_16x16x32_bf16 v[84:87], v[174:177], v[182:185], v[84:87]
	s_waitcnt vmcnt(15)
	ds_write_b128 v9, v[36:39] offset:53248
	v_add_co_u32_e32 v36, vcc, s8, v150
	s_nop 1
	v_addc_co_u32_e32 v37, vcc, 0, v151, vcc
	global_load_dwordx4 v[36:39], v[36:37], off offset:1920
	ds_read_b128 v[154:157], v252 offset:17408
	ds_read_b128 v[158:161], v252 offset:19456
	ds_read_b128 v[100:103], v251 offset:1024
	ds_read_b128 v[104:107], v251 offset:3072
	ds_read_b128 v[170:173], v252 offset:21504
	ds_read_b128 v[184:187], v252 offset:23552
	ds_read_b128 v[236:239], v251 offset:5120
	ds_read_b128 v[240:243], v251 offset:7168
	s_waitcnt lgkmcnt(5)
	v_mfma_f32_16x16x32_bf16 v[176:179], v[154:157], v[100:103], v[144:147]
	v_mfma_f32_16x16x32_bf16 v[180:183], v[158:161], v[100:103], v[140:143]
	s_waitcnt lgkmcnt(3)
	v_mfma_f32_16x16x32_bf16 v[232:235], v[170:173], v[100:103], v[136:139]
	s_waitcnt lgkmcnt(2)
	v_mfma_f32_16x16x32_bf16 v[244:247], v[184:187], v[100:103], v[132:135]
	s_mov_b32 s8, 0x20000
	s_waitcnt vmcnt(15)
	ds_write_b128 v9, v[32:35] offset:40960
	v_add_co_u32_e32 v32, vcc, s8, v152
	s_nop 1
	v_addc_co_u32_e32 v33, vcc, 0, v153, vcc
	global_load_dwordx4 v[32:35], v[32:33], off offset:1920
	v_mfma_f32_16x16x32_bf16 v[132:135], v[154:157], v[104:107], v[128:131]
	v_mfma_f32_16x16x32_bf16 v[136:139], v[158:161], v[104:107], v[124:127]
	v_mfma_f32_16x16x32_bf16 v[140:143], v[170:173], v[104:107], v[120:123]
	v_mfma_f32_16x16x32_bf16 v[144:147], v[184:187], v[104:107], v[116:119]
	s_waitcnt vmcnt(15)
	ds_write_b128 v9, v[44:47] offset:57344
	v_add_co_u32_e32 v44, vcc, s8, v150
	s_nop 1
	v_addc_co_u32_e32 v45, vcc, 0, v151, vcc
	global_load_dwordx4 v[44:47], v[44:45], off offset:1920
	s_waitcnt lgkmcnt(3)
	v_mfma_f32_16x16x32_bf16 v[100:103], v[154:157], v[236:239], v[112:115]
	v_mfma_f32_16x16x32_bf16 v[104:107], v[158:161], v[236:239], v[108:111]
	v_mfma_f32_16x16x32_bf16 v[108:111], v[170:173], v[236:239], v[162:165]
	v_mfma_f32_16x16x32_bf16 v[112:115], v[184:187], v[236:239], v[166:169]
	s_mov_b32 s8, 0x30000
	s_waitcnt vmcnt(15)
	ds_write_b128 v9, v[40:43] offset:45056
	v_add_co_u32_e32 v40, vcc, s8, v152
	s_nop 1
	v_addc_co_u32_e32 v41, vcc, 0, v153, vcc
	global_load_dwordx4 v[40:43], v[40:41], off offset:1920
	s_waitcnt lgkmcnt(3)
	v_mfma_f32_16x16x32_bf16 v[116:119], v[154:157], v[240:243], v[96:99]
	v_mfma_f32_16x16x32_bf16 v[120:123], v[158:161], v[240:243], v[92:95]
	v_mfma_f32_16x16x32_bf16 v[124:127], v[170:173], v[240:243], v[88:91]
	v_mfma_f32_16x16x32_bf16 v[128:131], v[184:187], v[240:243], v[84:87]
	s_waitcnt vmcnt(15)
	ds_write_b128 v9, v[48:51] offset:61440
	v_add_co_u32_e32 v48, vcc, s8, v150
	s_nop 1
	v_addc_co_u32_e32 v49, vcc, 0, v151, vcc
	global_load_dwordx4 v[48:51], v[48:49], off offset:1920
	s_setprio 0
	v_lshl_add_u64 v[188:189], s[2:3], 0, v[148:149]
	s_waitcnt lgkmcnt(0)
	s_barrier
	s_setprio 1
	ds_read_b128 v[148:151], v231 offset:49152
	ds_read_b128 v[152:155], v231 offset:51200
	ds_read_b128 v[96:99], v13 offset:32768
	ds_read_b128 v[172:175], v13 offset:34816
	ds_read_b128 v[156:159], v231 offset:53248
	ds_read_b128 v[160:163], v231 offset:55296
	ds_read_b128 v[168:171], v13 offset:36864
	ds_read_b128 v[164:167], v13 offset:38912
	s_waitcnt lgkmcnt(5)
	v_mfma_f32_16x16x32_bf16 v[84:87], v[148:151], v[96:99], v[176:179]
	v_mfma_f32_16x16x32_bf16 v[88:91], v[152:155], v[96:99], v[180:183]
	s_waitcnt lgkmcnt(3)
	v_mfma_f32_16x16x32_bf16 v[92:95], v[156:159], v[96:99], v[232:235]
	s_waitcnt lgkmcnt(2)
	v_mfma_f32_16x16x32_bf16 v[96:99], v[160:163], v[96:99], v[244:247]
	v_readlane_b32 s34, v248, 25
	s_and_b64 vcc, exec, s[40:41]
	v_readlane_b32 s35, v248, 26
	s_waitcnt vmcnt(15)
	ds_write_b128 v9, v[52:55]
	s_cbranch_vccnz .LBB0_199
	global_load_dwordx4 v[52:55], v[188:189], off

.LBB0_205:
	ds_read_b128 v[148:151], v252 offset:50176
	ds_read_b128 v[152:155], v252 offset:52224
	ds_read_b128 v[176:179], v251 offset:33792
	ds_read_b128 v[172:175], v251 offset:35840
	ds_read_b128 v[156:159], v252 offset:54272
	ds_read_b128 v[160:163], v252 offset:56320
	ds_read_b128 v[168:171], v251 offset:37888
	ds_read_b128 v[164:167], v251 offset:39936
	s_waitcnt lgkmcnt(5)
	v_mfma_f32_16x16x32_bf16 v[84:87], v[148:151], v[176:179], v[84:87]
	v_mfma_f32_16x16x32_bf16 v[88:91], v[152:155], v[176:179], v[88:91]
	s_waitcnt lgkmcnt(3)
	v_mfma_f32_16x16x32_bf16 v[92:95], v[156:159], v[176:179], v[92:95]
	s_waitcnt lgkmcnt(2)
	v_mfma_f32_16x16x32_bf16 v[96:99], v[160:163], v[176:179], v[96:99]
	s_and_b64 vcc, exec, s[40:41]
	s_waitcnt vmcnt(11)
	ds_write_b128 v9, v[64:67] offset:8192
	s_cbranch_vccnz .LBB0_207
	v_add_co_u32_e32 v64, vcc, 0x20000, v188
	s_nop 1
	v_addc_co_u32_e32 v65, vcc, 0, v189, vcc
	global_load_dwordx4 v[64:67], v[64:65], off

.LBB0_221:
	ds_read_b128 v[148:151], v252 offset:17408
	ds_read_b128 v[152:155], v252 offset:19456
	ds_read_b128 v[176:179], v251 offset:1024
	ds_read_b128 v[172:175], v251 offset:3072
	ds_read_b128 v[156:159], v252 offset:21504
	ds_read_b128 v[160:163], v252 offset:23552
	ds_read_b128 v[168:171], v251 offset:5120
	ds_read_b128 v[164:167], v251 offset:7168
	s_waitcnt lgkmcnt(5)
	v_mfma_f32_16x16x32_bf16 v[84:87], v[148:151], v[176:179], v[84:87]
	v_mfma_f32_16x16x32_bf16 v[88:91], v[152:155], v[176:179], v[88:91]
	s_waitcnt lgkmcnt(3)
	v_mfma_f32_16x16x32_bf16 v[92:95], v[156:159], v[176:179], v[92:95]
	s_waitcnt lgkmcnt(2)
	v_mfma_f32_16x16x32_bf16 v[96:99], v[160:163], v[176:179], v[96:99]
	s_and_b64 vcc, exec, s[40:41]
	s_waitcnt vmcnt(3)
	ds_write_b128 v9, v[32:35] offset:40960
	s_cbranch_vccnz .LBB0_223
	v_add_co_u32_e32 v32, vcc, 0x20000, v188
	s_nop 1
	v_addc_co_u32_e32 v33, vcc, 0, v189, vcc
	global_load_dwordx4 v[32:35], v[32:33], off offset:128

.LBB0_237:
	ds_read_b128 v[168:171], v252 offset:50176
	ds_read_b128 v[172:175], v252 offset:52224
	ds_read_b128 v[132:135], v251 offset:33792
	ds_read_b128 v[128:131], v251 offset:35840
	ds_read_b128 v[176:179], v252 offset:54272
	ds_read_b128 v[180:183], v252 offset:56320
	s_waitcnt lgkmcnt(3)
	v_mfma_f32_16x16x32_bf16 v[144:147], v[172:175], v[132:135], v[88:91]
	v_mfma_f32_16x16x32_bf16 v[148:151], v[168:171], v[132:135], v[84:87]
	s_waitcnt lgkmcnt(1)
	v_mfma_f32_16x16x32_bf16 v[88:91], v[176:179], v[132:135], v[160:163]
	ds_read_b128 v[184:187], v251 offset:37888
	s_nop 1
	ds_read_b128 v[160:163], v251 offset:39936
	s_waitcnt lgkmcnt(2)
	v_mfma_f32_16x16x32_bf16 v[84:87], v[180:183], v[132:135], v[164:167]
	s_and_b64 vcc, exec, s[40:41]
	s_cbranch_vccnz .LBB0_239
	ds_write_b128 v9, v[64:67] offset:8192
	v_add_co_u32_e32 v64, vcc, 0x20000, v188
	s_nop 1
	v_addc_co_u32_e32 v65, vcc, 0, v189, vcc
	global_load_dwordx4 v[64:67], v[64:65], off offset:256

.LBB0_646:
	s_ashr_i32 s10, s3, 4
	s_and_b32 s11, s3, 7
	s_and_b64 s[8:9], s[76:77], exec
	s_cselect_b32 s42, s10, s11
	s_ashr_i32 s41, s40, 31
	s_ashr_i32 s43, s42, 31
	s_lshl_b64 s[8:9], s[40:41], 18
	s_lshl_b64 s[10:11], s[42:43], 18
	s_add_u32 s20, s6, s8
	s_addc_u32 s21, s7, s9
	v_mov_b32_e32 v84, v197
	s_add_u32 s34, s14, s10
	s_addc_u32 s35, s15, s11
	v_ashrrev_i32_e32 v4, 3, v84
	v_readlane_b32 s19, v248, 0
	v_and_b32_e32 v5, 7, v84
	v_lshlrev_b32_e32 v9, 6, v4
	s_cmp_lg_u32 s3, s19
	v_lshlrev_b32_e32 v85, 3, v5
	v_lshrrev_b32_e32 v5, 6, v84
	v_bfe_u32 v8, v84, 2, 1
	v_and_b32_e32 v9, 0x3c0, v9
	v_lshlrev_b32_e32 v12, 4, v84
	s_mov_b32 s3, 0x3ffffe
	v_and_or_b32 v9, v12, 48, v9
	v_lshlrev_b32_e32 v12, 2, v4
	v_and_or_b32 v5, v5, s3, v8
	v_and_b32_e32 v12, 32, v12
	v_lshlrev_b32_e32 v86, 10, v4
	v_lshlrev_b32_e32 v5, 10, v5
	v_or_b32_e32 v4, v86, v85
	v_bitop3_b32 v230, v9, v5, v12 bitop3:0xde
	v_and_b32_e32 v253, 4, v197
	v_lshlrev_b32_e32 v253, 4, v253
	v_add_u32_e32 v253, v253, v230
	v_and_b32_e32 v253, 0x3ff, v253
	v_and_b32_e32 v230, 0xfffffc00, v230
	v_or_b32_e32 v230, v230, v253
	v_mov_b32_e32 v5, v2
	v_lshlrev_b64 v[8:9], 1, v[4:5]
	v_lshl_add_u64 v[16:17], s[20:21], 0, v[8:9]
	v_lshl_add_u64 v[12:13], s[34:35], 0, v[8:9]
	s_cbranch_scc1 .LBB0_648
	v_add_co_u32_e32 v88, vcc, 0x10000, v16
	global_load_dwordx4 v[52:55], v[16:17], off
	global_load_dwordx4 v[56:59], v[12:13], off
	v_addc_co_u32_e32 v89, vcc, 0, v17, vcc
	v_add_co_u32_e32 v90, vcc, 0x10000, v12
	global_load_dwordx4 v[60:63], v[88:89], off
	s_nop 0
	v_addc_co_u32_e32 v91, vcc, 0, v13, vcc
	v_add_co_u32_e32 v92, vcc, 0x20000, v16
	global_load_dwordx4 v[64:67], v[90:91], off
	s_nop 0
	v_addc_co_u32_e32 v93, vcc, 0, v17, vcc
	v_add_co_u32_e32 v94, vcc, 0x20000, v12
	global_load_dwordx4 v[68:71], v[92:93], off
	s_nop 0
	v_addc_co_u32_e32 v95, vcc, 0, v13, vcc
	v_add_co_u32_e32 v96, vcc, 0x30000, v16
	global_load_dwordx4 v[72:75], v[94:95], off
	s_nop 0
	v_addc_co_u32_e32 v97, vcc, 0, v17, vcc
	global_load_dwordx4 v[76:79], v[96:97], off
	v_add_co_u32_e32 v98, vcc, 0x30000, v12
	s_nop 1
	v_addc_co_u32_e32 v99, vcc, 0, v13, vcc
	global_load_dwordx4 v[80:83], v[98:99], off
	global_load_dwordx4 v[20:23], v[16:17], off offset:128
	global_load_dwordx4 v[24:27], v[12:13], off offset:128
	global_load_dwordx4 v[28:31], v[88:89], off offset:128
	global_load_dwordx4 v[36:39], v[90:91], off offset:128
	global_load_dwordx4 v[32:35], v[92:93], off offset:128
	global_load_dwordx4 v[44:47], v[94:95], off offset:128
	global_load_dwordx4 v[40:43], v[96:97], off offset:128
	global_load_dwordx4 v[48:51], v[98:99], off offset:128
	s_barrier
	s_waitcnt vmcnt(15)
	ds_write_b128 v230, v[52:55]
	s_waitcnt vmcnt(14)
	ds_write_b128 v230, v[56:59] offset:16384
	s_waitcnt vmcnt(13)
	ds_write_b128 v230, v[60:63] offset:4096
	s_waitcnt vmcnt(12)
	ds_write_b128 v230, v[64:67] offset:20480
	s_waitcnt vmcnt(11)
	ds_write_b128 v230, v[68:71] offset:8192
	s_waitcnt vmcnt(10)
	ds_write_b128 v230, v[72:75] offset:24576
	s_waitcnt vmcnt(9)
	ds_write_b128 v230, v[76:79] offset:12288
	s_waitcnt vmcnt(8)
	ds_write_b128 v230, v[80:83] offset:28672
	global_load_dwordx4 v[52:55], v[16:17], off offset:256
	global_load_dwordx4 v[56:59], v[12:13], off offset:256
	global_load_dwordx4 v[60:63], v[88:89], off offset:256
	global_load_dwordx4 v[68:71], v[90:91], off offset:256
	global_load_dwordx4 v[64:67], v[92:93], off offset:256
	global_load_dwordx4 v[76:79], v[94:95], off offset:256
	global_load_dwordx4 v[72:75], v[96:97], off offset:256
	global_load_dwordx4 v[80:83], v[98:99], off offset:256
.LBB0_648:
	v_lshlrev_b32_e32 v87, 6, v84
	v_lshlrev_b32_e32 v89, 2, v84
	s_add_u32 s10, s16, s10
	v_and_b32_e32 v88, 0x3c0, v87
	v_and_b32_e32 v89, 32, v89
	v_and_b32_e32 v90, 48, v84
	v_lshlrev_b32_e32 v84, 7, v84
	s_addc_u32 s11, s17, s11
	v_bitop3_b32 v88, v88, v89, v90 bitop3:0x36
	v_and_b32_e32 v89, 0x2000, v84
	v_add_u32_e32 v84, v86, v85
	v_mov_b32_e32 v85, v2
	s_add_u32 s8, s24, s8
	v_lshlrev_b64 v[84:85], 1, v[84:85]
	s_addc_u32 s9, s25, s9
	v_and_b32_e32 v87, 0xffffe000, v87
	v_lshl_add_u64 v[148:149], s[10:11], 0, v[84:85]
	v_lshl_add_u64 v[150:151], s[8:9], 0, v[84:85]
	v_mov_b32_e32 v84, 0
	s_mov_b64 s[8:9], 0
	v_add_u32_e32 v231, v88, v87
	v_add_u32_e32 v232, v88, v89
	v_add_u32_e32 v253, 64, v231
	v_and_b32_e32 v253, 0x3ff, v253
	v_and_b32_e32 v251, 0xfffffc00, v231
	v_or_b32_e32 v251, v251, v253
	v_add_u32_e32 v253, 64, v232
	v_and_b32_e32 v253, 0x3ff, v253
	v_and_b32_e32 v252, 0xfffffc00, v232
	v_or_b32_e32 v252, v252, v253
	v_mov_b32_e32 v85, v84
	v_mov_b32_e32 v86, v84
	v_mov_b32_e32 v87, v84
	v_mov_b32_e32 v88, v84
	v_mov_b32_e32 v89, v84
	v_mov_b32_e32 v90, v84
	v_mov_b32_e32 v91, v84
	v_mov_b32_e32 v92, v84
	v_mov_b32_e32 v93, v84
	v_mov_b32_e32 v94, v84
	v_mov_b32_e32 v95, v84
	v_mov_b32_e32 v96, v84
	v_mov_b32_e32 v97, v84
	v_mov_b32_e32 v98, v84
	v_mov_b32_e32 v99, v84
	v_mov_b32_e32 v100, v84
	v_mov_b32_e32 v101, v84
	v_mov_b32_e32 v102, v84
	v_mov_b32_e32 v103, v84
	v_mov_b32_e32 v104, v84
	v_mov_b32_e32 v105, v84
	v_mov_b32_e32 v106, v84
	v_mov_b32_e32 v107, v84
	v_mov_b32_e32 v108, v84
	v_mov_b32_e32 v109, v84
	v_mov_b32_e32 v110, v84
	v_mov_b32_e32 v111, v84
	v_mov_b32_e32 v112, v84
	v_mov_b32_e32 v113, v84
	v_mov_b32_e32 v114, v84
	v_mov_b32_e32 v115, v84
	v_mov_b32_e32 v116, v84
	v_mov_b32_e32 v117, v84
	v_mov_b32_e32 v118, v84
	v_mov_b32_e32 v119, v84
	v_mov_b32_e32 v120, v84
	v_mov_b32_e32 v121, v84
	v_mov_b32_e32 v122, v84
	v_mov_b32_e32 v123, v84
	v_mov_b32_e32 v124, v84
	v_mov_b32_e32 v125, v84
	v_mov_b32_e32 v126, v84
	v_mov_b32_e32 v127, v84
	v_mov_b32_e32 v128, v84
	v_mov_b32_e32 v129, v84
	v_mov_b32_e32 v130, v84
	v_mov_b32_e32 v131, v84
	v_mov_b32_e32 v132, v84
	v_mov_b32_e32 v133, v84
	v_mov_b32_e32 v134, v84
	v_mov_b32_e32 v135, v84
	v_mov_b32_e32 v136, v84
	v_mov_b32_e32 v137, v84
	v_mov_b32_e32 v138, v84
	v_mov_b32_e32 v139, v84
	v_mov_b32_e32 v140, v84
	v_mov_b32_e32 v141, v84
	v_mov_b32_e32 v142, v84
	v_mov_b32_e32 v143, v84
	v_mov_b32_e32 v144, v84
	v_mov_b32_e32 v145, v84
	v_mov_b32_e32 v146, v84
	v_mov_b32_e32 v147, v84
	s_waitcnt lgkmcnt(0)
	s_barrier
.LBB0_649:
	v_lshl_add_u64 v[184:185], v[150:151], 0, s[8:9]
	v_lshl_add_u64 v[186:187], v[148:149], 0, s[8:9]
	s_setprio 1
	ds_read_b128 v[152:155], v232 offset:16384
	ds_read_b128 v[156:159], v232 offset:18432
	ds_read_b128 v[160:163], v231
	ds_read_b128 v[164:167], v231 offset:2048
	ds_read_b128 v[168:171], v232 offset:20480
	ds_read_b128 v[172:175], v232 offset:22528
	ds_read_b128 v[176:179], v231 offset:4096
	ds_read_b128 v[180:183], v231 offset:6144
	s_waitcnt lgkmcnt(5)
	v_mfma_f32_16x16x32_bf16 v[144:147], v[152:155], v[160:163], v[144:147]
	v_mfma_f32_16x16x32_bf16 v[140:143], v[156:159], v[160:163], v[140:143]
	s_waitcnt lgkmcnt(3)
	v_mfma_f32_16x16x32_bf16 v[136:139], v[168:171], v[160:163], v[136:139]
	s_waitcnt lgkmcnt(2)
	v_mfma_f32_16x16x32_bf16 v[132:135], v[172:175], v[160:163], v[132:135]
	v_add_co_u32_e32 v188, vcc, s27, v184
	s_waitcnt vmcnt(15)
	ds_write_b128 v230, v[20:23] offset:32768
	v_addc_co_u32_e32 v189, vcc, 0, v185, vcc
	global_load_dwordx4 v[20:23], v[188:189], off offset:384
	v_mfma_f32_16x16x32_bf16 v[128:131], v[152:155], v[164:167], v[128:131]
	v_mfma_f32_16x16x32_bf16 v[124:127], v[156:159], v[164:167], v[124:127]
	v_mfma_f32_16x16x32_bf16 v[120:123], v[168:171], v[164:167], v[120:123]
	v_mfma_f32_16x16x32_bf16 v[116:119], v[172:175], v[164:167], v[116:119]
	s_mov_b32 s3, 0xd88000
	v_add_co_u32_e32 v190, vcc, s3, v186
	s_waitcnt vmcnt(15)
	ds_write_b128 v230, v[24:27] offset:49152
	v_addc_co_u32_e32 v191, vcc, 0, v187, vcc
	global_load_dwordx4 v[24:27], v[190:191], off offset:384
	s_waitcnt lgkmcnt(3)
	v_mfma_f32_16x16x32_bf16 v[112:115], v[152:155], v[176:179], v[112:115]
	v_mfma_f32_16x16x32_bf16 v[108:111], v[156:159], v[176:179], v[108:111]
	v_mfma_f32_16x16x32_bf16 v[104:107], v[168:171], v[176:179], v[104:107]
	v_mfma_f32_16x16x32_bf16 v[100:103], v[172:175], v[176:179], v[100:103]
	v_add_co_u32_e32 v234, vcc, s30, v184
	s_waitcnt vmcnt(15)
	ds_write_b128 v230, v[28:31] offset:36864
	v_addc_co_u32_e32 v235, vcc, 0, v185, vcc
	global_load_dwordx4 v[28:31], v[234:235], off offset:384
	s_waitcnt lgkmcnt(3)
	v_mfma_f32_16x16x32_bf16 v[96:99], v[152:155], v[180:183], v[96:99]
	v_mfma_f32_16x16x32_bf16 v[92:95], v[156:159], v[180:183], v[92:95]
	v_mfma_f32_16x16x32_bf16 v[88:91], v[168:171], v[180:183], v[88:91]
	v_mfma_f32_16x16x32_bf16 v[84:87], v[172:175], v[180:183], v[84:87]
	s_mov_b32 s3, 0xd98000
	v_add_co_u32_e32 v236, vcc, s3, v186
	s_waitcnt vmcnt(15)
	ds_write_b128 v230, v[36:39] offset:53248
	v_addc_co_u32_e32 v237, vcc, 0, v187, vcc
	global_load_dwordx4 v[36:39], v[236:237], off offset:384
	ds_read_b128 v[152:155], v252 offset:17408
	ds_read_b128 v[156:159], v252 offset:19456
	ds_read_b128 v[160:163], v251 offset:1024
	ds_read_b128 v[164:167], v251 offset:3072
	ds_read_b128 v[168:171], v252 offset:21504
	ds_read_b128 v[172:175], v252 offset:23552
	ds_read_b128 v[176:179], v251 offset:5120
	ds_read_b128 v[180:183], v251 offset:7168
	s_waitcnt lgkmcnt(5)
	v_mfma_f32_16x16x32_bf16 v[144:147], v[152:155], v[160:163], v[144:147]
	v_mfma_f32_16x16x32_bf16 v[140:143], v[156:159], v[160:163], v[140:143]
	s_waitcnt lgkmcnt(3)
	v_mfma_f32_16x16x32_bf16 v[136:139], v[168:171], v[160:163], v[136:139]
	s_waitcnt lgkmcnt(2)
	v_mfma_f32_16x16x32_bf16 v[132:135], v[172:175], v[160:163], v[132:135]
	v_add_co_u32_e32 v238, vcc, s31, v184
	s_waitcnt vmcnt(15)
	ds_write_b128 v230, v[32:35] offset:40960
	v_addc_co_u32_e32 v239, vcc, 0, v185, vcc
	global_load_dwordx4 v[32:35], v[238:239], off offset:384
	v_mfma_f32_16x16x32_bf16 v[128:131], v[152:155], v[164:167], v[128:131]
	v_mfma_f32_16x16x32_bf16 v[124:127], v[156:159], v[164:167], v[124:127]
	v_mfma_f32_16x16x32_bf16 v[120:123], v[168:171], v[164:167], v[120:123]
	v_mfma_f32_16x16x32_bf16 v[116:119], v[172:175], v[164:167], v[116:119]
	s_mov_b32 s3, 0xda8000
	v_add_co_u32_e32 v240, vcc, s3, v186
	s_waitcnt vmcnt(15)
	ds_write_b128 v230, v[44:47] offset:57344
	v_addc_co_u32_e32 v241, vcc, 0, v187, vcc
	global_load_dwordx4 v[44:47], v[240:241], off offset:384
	s_waitcnt lgkmcnt(3)
	v_mfma_f32_16x16x32_bf16 v[112:115], v[152:155], v[176:179], v[112:115]
	v_mfma_f32_16x16x32_bf16 v[108:111], v[156:159], v[176:179], v[108:111]
	v_mfma_f32_16x16x32_bf16 v[104:107], v[168:171], v[176:179], v[104:107]
	v_mfma_f32_16x16x32_bf16 v[100:103], v[172:175], v[176:179], v[100:103]
	v_add_co_u32_e32 v184, vcc, s92, v184
	s_waitcnt vmcnt(15)
	ds_write_b128 v230, v[40:43] offset:45056
	v_addc_co_u32_e32 v185, vcc, 0, v185, vcc
	global_load_dwordx4 v[40:43], v[184:185], off offset:384
	s_waitcnt lgkmcnt(3)
	v_mfma_f32_16x16x32_bf16 v[96:99], v[152:155], v[180:183], v[96:99]
	v_mfma_f32_16x16x32_bf16 v[92:95], v[156:159], v[180:183], v[92:95]
	v_mfma_f32_16x16x32_bf16 v[88:91], v[168:171], v[180:183], v[88:91]
	v_mfma_f32_16x16x32_bf16 v[84:87], v[172:175], v[180:183], v[84:87]
	s_mov_b32 s3, 0xdb8000
	v_add_co_u32_e32 v186, vcc, s3, v186
	s_waitcnt vmcnt(15)
	ds_write_b128 v230, v[48:51] offset:61440
	v_addc_co_u32_e32 v187, vcc, 0, v187, vcc
	global_load_dwordx4 v[48:51], v[186:187], off offset:384
	s_setprio 0
	s_waitcnt lgkmcnt(0)
	s_barrier
	s_setprio 1
	ds_read_b128 v[152:155], v232 offset:49152
	ds_read_b128 v[156:159], v232 offset:51200
	ds_read_b128 v[160:163], v231 offset:32768
	ds_read_b128 v[164:167], v231 offset:34816
	ds_read_b128 v[168:171], v232 offset:53248
	ds_read_b128 v[172:175], v232 offset:55296
	ds_read_b128 v[176:179], v231 offset:36864
	ds_read_b128 v[180:183], v231 offset:38912
	s_waitcnt lgkmcnt(5)
	v_mfma_f32_16x16x32_bf16 v[144:147], v[152:155], v[160:163], v[144:147]
	v_mfma_f32_16x16x32_bf16 v[140:143], v[156:159], v[160:163], v[140:143]
	s_waitcnt lgkmcnt(3)
	v_mfma_f32_16x16x32_bf16 v[136:139], v[168:171], v[160:163], v[136:139]
	s_waitcnt lgkmcnt(2)
	v_mfma_f32_16x16x32_bf16 v[132:135], v[172:175], v[160:163], v[132:135]
	s_waitcnt vmcnt(15)
	ds_write_b128 v230, v[52:55]
	global_load_dwordx4 v[52:55], v[188:189], off offset:512
	v_mfma_f32_16x16x32_bf16 v[128:131], v[152:155], v[164:167], v[128:131]
	v_mfma_f32_16x16x32_bf16 v[124:127], v[156:159], v[164:167], v[124:127]
	v_mfma_f32_16x16x32_bf16 v[120:123], v[168:171], v[164:167], v[120:123]
	v_mfma_f32_16x16x32_bf16 v[116:119], v[172:175], v[164:167], v[116:119]
	s_waitcnt vmcnt(15)
	ds_write_b128 v230, v[56:59] offset:16384
	global_load_dwordx4 v[56:59], v[190:191], off offset:512
	s_waitcnt lgkmcnt(3)
	v_mfma_f32_16x16x32_bf16 v[112:115], v[152:155], v[176:179], v[112:115]
	v_mfma_f32_16x16x32_bf16 v[108:111], v[156:159], v[176:179], v[108:111]
	v_mfma_f32_16x16x32_bf16 v[104:107], v[168:171], v[176:179], v[104:107]
	v_mfma_f32_16x16x32_bf16 v[100:103], v[172:175], v[176:179], v[100:103]
	s_waitcnt vmcnt(15)
	ds_write_b128 v230, v[60:63] offset:4096
	global_load_dwordx4 v[60:63], v[234:235], off offset:512
	s_waitcnt lgkmcnt(3)
	v_mfma_f32_16x16x32_bf16 v[96:99], v[152:155], v[180:183], v[96:99]
	v_mfma_f32_16x16x32_bf16 v[92:95], v[156:159], v[180:183], v[92:95]
	v_mfma_f32_16x16x32_bf16 v[88:91], v[168:171], v[180:183], v[88:91]
	v_mfma_f32_16x16x32_bf16 v[84:87], v[172:175], v[180:183], v[84:87]
	s_waitcnt vmcnt(15)
	ds_write_b128 v230, v[68:71] offset:20480
	global_load_dwordx4 v[68:71], v[236:237], off offset:512
	ds_read_b128 v[152:155], v252 offset:50176
	ds_read_b128 v[156:159], v252 offset:52224
	ds_read_b128 v[160:163], v251 offset:33792
	ds_read_b128 v[164:167], v251 offset:35840
	ds_read_b128 v[168:171], v252 offset:54272
	ds_read_b128 v[172:175], v252 offset:56320
	ds_read_b128 v[176:179], v251 offset:37888
	ds_read_b128 v[180:183], v251 offset:39936
	s_waitcnt lgkmcnt(5)
	v_mfma_f32_16x16x32_bf16 v[144:147], v[152:155], v[160:163], v[144:147]
	v_mfma_f32_16x16x32_bf16 v[140:143], v[156:159], v[160:163], v[140:143]
	s_waitcnt lgkmcnt(3)
	v_mfma_f32_16x16x32_bf16 v[136:139], v[168:171], v[160:163], v[136:139]
	s_waitcnt lgkmcnt(2)
	v_mfma_f32_16x16x32_bf16 v[132:135], v[172:175], v[160:163], v[132:135]
	s_waitcnt vmcnt(15)
	ds_write_b128 v230, v[64:67] offset:8192
	global_load_dwordx4 v[64:67], v[238:239], off offset:512
	v_mfma_f32_16x16x32_bf16 v[128:131], v[152:155], v[164:167], v[128:131]
	v_mfma_f32_16x16x32_bf16 v[124:127], v[156:159], v[164:167], v[124:127]
	v_mfma_f32_16x16x32_bf16 v[120:123], v[168:171], v[164:167], v[120:123]
	v_mfma_f32_16x16x32_bf16 v[116:119], v[172:175], v[164:167], v[116:119]
	s_waitcnt vmcnt(15)
	ds_write_b128 v230, v[76:79] offset:24576
	global_load_dwordx4 v[76:79], v[240:241], off offset:512
	s_waitcnt lgkmcnt(3)
	v_mfma_f32_16x16x32_bf16 v[112:115], v[152:155], v[176:179], v[112:115]
	v_mfma_f32_16x16x32_bf16 v[108:111], v[156:159], v[176:179], v[108:111]
	v_mfma_f32_16x16x32_bf16 v[104:107], v[168:171], v[176:179], v[104:107]
	v_mfma_f32_16x16x32_bf16 v[100:103], v[172:175], v[176:179], v[100:103]
	s_waitcnt vmcnt(15)
	ds_write_b128 v230, v[72:75] offset:12288
	global_load_dwordx4 v[72:75], v[184:185], off offset:512
	s_waitcnt lgkmcnt(3)
	v_mfma_f32_16x16x32_bf16 v[96:99], v[152:155], v[180:183], v[96:99]
	v_mfma_f32_16x16x32_bf16 v[92:95], v[156:159], v[180:183], v[92:95]
	v_mfma_f32_16x16x32_bf16 v[88:91], v[168:171], v[180:183], v[88:91]
	v_mfma_f32_16x16x32_bf16 v[84:87], v[172:175], v[180:183], v[84:87]
	s_waitcnt vmcnt(15)
	ds_write_b128 v230, v[80:83] offset:28672
	global_load_dwordx4 v[80:83], v[186:187], off offset:512
	s_setprio 0
	s_add_u32 s8, s8, 0x100
	s_addc_u32 s9, s9, 0
	s_cmpk_eq_i32 s8, 0x600
	s_waitcnt lgkmcnt(0)
	s_barrier
	s_cbranch_scc0 .LBB0_649
	s_ashr_i32 s3, s2, 31
	s_lshl_b64 s[2:3], s[2:3], 18
	s_add_u32 s2, s6, s2
	s_addc_u32 s3, s7, s3
	s_setprio 1
	ds_read_b128 v[148:151], v232 offset:16384
	ds_read_b128 v[152:155], v232 offset:18432
	ds_read_b128 v[156:159], v231
	ds_read_b128 v[160:163], v231 offset:2048
	ds_read_b128 v[164:167], v232 offset:20480
	ds_read_b128 v[168:171], v232 offset:22528
	ds_read_b128 v[172:175], v231 offset:4096
	ds_read_b128 v[176:179], v231 offset:6144
	s_waitcnt lgkmcnt(5)
	v_mfma_f32_16x16x32_bf16 v[144:147], v[148:151], v[156:159], v[144:147]
	v_mfma_f32_16x16x32_bf16 v[140:143], v[152:155], v[156:159], v[140:143]
	s_waitcnt lgkmcnt(3)
	v_mfma_f32_16x16x32_bf16 v[136:139], v[164:167], v[156:159], v[136:139]
	s_waitcnt lgkmcnt(2)
	v_mfma_f32_16x16x32_bf16 v[132:135], v[168:171], v[156:159], v[132:135]
	s_waitcnt vmcnt(15)
	ds_write_b128 v230, v[20:23] offset:32768
	global_load_dwordx4 v[20:23], v[16:17], off offset:1920
	v_mfma_f32_16x16x32_bf16 v[128:131], v[148:151], v[160:163], v[128:131]
	v_mfma_f32_16x16x32_bf16 v[124:127], v[152:155], v[160:163], v[124:127]
	v_mfma_f32_16x16x32_bf16 v[120:123], v[164:167], v[160:163], v[120:123]
	v_mfma_f32_16x16x32_bf16 v[116:119], v[168:171], v[160:163], v[116:119]
	s_waitcnt vmcnt(15)
	ds_write_b128 v230, v[24:27] offset:49152
	global_load_dwordx4 v[24:27], v[12:13], off offset:1920
	s_waitcnt lgkmcnt(3)
	v_mfma_f32_16x16x32_bf16 v[112:115], v[148:151], v[172:175], v[112:115]
	v_mfma_f32_16x16x32_bf16 v[108:111], v[152:155], v[172:175], v[108:111]
	v_mfma_f32_16x16x32_bf16 v[156:159], v[164:167], v[172:175], v[104:107]
	v_mfma_f32_16x16x32_bf16 v[160:163], v[168:171], v[172:175], v[100:103]
	s_mov_b32 s8, 0x10000
	s_waitcnt vmcnt(15)
	ds_write_b128 v230, v[28:31] offset:36864
	v_add_co_u32_e32 v28, vcc, s8, v16
	s_nop 1
	v_addc_co_u32_e32 v29, vcc, 0, v17, vcc
	global_load_dwordx4 v[28:31], v[28:29], off offset:1920
	s_waitcnt lgkmcnt(3)
	v_mfma_f32_16x16x32_bf16 v[96:99], v[148:151], v[176:179], v[96:99]
	v_mfma_f32_16x16x32_bf16 v[92:95], v[152:155], v[176:179], v[92:95]
	v_mfma_f32_16x16x32_bf16 v[88:91], v[164:167], v[176:179], v[88:91]
	v_mfma_f32_16x16x32_bf16 v[84:87], v[168:171], v[176:179], v[84:87]
	s_waitcnt vmcnt(15)
	ds_write_b128 v230, v[36:39] offset:53248
	v_add_co_u32_e32 v36, vcc, s8, v12
	s_nop 1
	v_addc_co_u32_e32 v37, vcc, 0, v13, vcc
	global_load_dwordx4 v[36:39], v[36:37], off offset:1920
	ds_read_b128 v[148:151], v252 offset:17408
	ds_read_b128 v[152:155], v252 offset:19456
	ds_read_b128 v[100:103], v251 offset:1024
	ds_read_b128 v[104:107], v251 offset:3072
	ds_read_b128 v[168:171], v252 offset:21504
	ds_read_b128 v[172:175], v252 offset:23552
	ds_read_b128 v[184:187], v251 offset:5120
	ds_read_b128 v[188:191], v251 offset:7168
	s_waitcnt lgkmcnt(5)
	v_mfma_f32_16x16x32_bf16 v[164:167], v[148:151], v[100:103], v[144:147]
	v_mfma_f32_16x16x32_bf16 v[176:179], v[152:155], v[100:103], v[140:143]
	s_waitcnt lgkmcnt(3)
	v_mfma_f32_16x16x32_bf16 v[180:183], v[168:171], v[100:103], v[136:139]
	s_waitcnt lgkmcnt(2)
	v_mfma_f32_16x16x32_bf16 v[234:237], v[172:175], v[100:103], v[132:135]
	s_mov_b32 s8, 0x20000
	s_waitcnt vmcnt(15)
	ds_write_b128 v230, v[32:35] offset:40960
	v_add_co_u32_e32 v32, vcc, s8, v16
	s_nop 1
	v_addc_co_u32_e32 v33, vcc, 0, v17, vcc
	global_load_dwordx4 v[32:35], v[32:33], off offset:1920
	v_mfma_f32_16x16x32_bf16 v[132:135], v[148:151], v[104:107], v[128:131]
	v_mfma_f32_16x16x32_bf16 v[136:139], v[152:155], v[104:107], v[124:127]
	v_mfma_f32_16x16x32_bf16 v[140:143], v[168:171], v[104:107], v[120:123]
	v_mfma_f32_16x16x32_bf16 v[144:147], v[172:175], v[104:107], v[116:119]
	s_waitcnt vmcnt(15)
	ds_write_b128 v230, v[44:47] offset:57344
	v_add_co_u32_e32 v44, vcc, s8, v12
	s_nop 1
	v_addc_co_u32_e32 v45, vcc, 0, v13, vcc
	global_load_dwordx4 v[44:47], v[44:45], off offset:1920
	s_waitcnt lgkmcnt(3)
	v_mfma_f32_16x16x32_bf16 v[100:103], v[148:151], v[184:187], v[112:115]
	v_mfma_f32_16x16x32_bf16 v[104:107], v[152:155], v[184:187], v[108:111]
	v_mfma_f32_16x16x32_bf16 v[108:111], v[168:171], v[184:187], v[156:159]
	v_mfma_f32_16x16x32_bf16 v[112:115], v[172:175], v[184:187], v[160:163]
	s_mov_b32 s8, 0x30000
	v_add_co_u32_e32 v16, vcc, s8, v16
	s_waitcnt vmcnt(15)
	ds_write_b128 v230, v[40:43] offset:45056
	v_addc_co_u32_e32 v17, vcc, 0, v17, vcc
	global_load_dwordx4 v[40:43], v[16:17], off offset:1920
	s_waitcnt lgkmcnt(3)
	v_mfma_f32_16x16x32_bf16 v[116:119], v[148:151], v[188:191], v[96:99]
	v_mfma_f32_16x16x32_bf16 v[120:123], v[152:155], v[188:191], v[92:95]
	v_mfma_f32_16x16x32_bf16 v[124:127], v[168:171], v[188:191], v[88:91]
	v_mfma_f32_16x16x32_bf16 v[128:131], v[172:175], v[188:191], v[84:87]
	v_add_co_u32_e32 v12, vcc, s8, v12
	s_waitcnt vmcnt(15)
	ds_write_b128 v230, v[48:51] offset:61440
	v_addc_co_u32_e32 v13, vcc, 0, v13, vcc
	global_load_dwordx4 v[48:51], v[12:13], off offset:1920
	s_setprio 0
	v_lshl_add_u64 v[8:9], s[2:3], 0, v[8:9]
	s_waitcnt lgkmcnt(0)
	s_barrier
	s_setprio 1
	ds_read_b128 v[148:151], v232 offset:49152
	ds_read_b128 v[152:155], v232 offset:51200
	ds_read_b128 v[96:99], v231 offset:32768
	ds_read_b128 v[172:175], v231 offset:34816
	ds_read_b128 v[156:159], v232 offset:53248
	ds_read_b128 v[160:163], v232 offset:55296
	s_waitcnt lgkmcnt(3)
	v_mfma_f32_16x16x32_bf16 v[84:87], v[148:151], v[96:99], v[164:167]
	ds_read_b128 v[168:171], v231 offset:36864
	s_nop 1
	ds_read_b128 v[164:167], v231 offset:38912
	v_mfma_f32_16x16x32_bf16 v[88:91], v[152:155], v[96:99], v[176:179]
	s_waitcnt lgkmcnt(3)
	v_mfma_f32_16x16x32_bf16 v[92:95], v[156:159], v[96:99], v[180:183]
	s_waitcnt lgkmcnt(2)
	v_mfma_f32_16x16x32_bf16 v[96:99], v[160:163], v[96:99], v[234:237]
	v_cndmask_b32_e64 v12, 0, 1, s[44:45]
	v_readlane_b32 s34, v248, 25
	v_cmp_ne_u32_e64 s[38:39], 1, v12
	s_andn2_b64 vcc, exec, s[44:45]
	v_readlane_b32 s35, v248, 26
	s_waitcnt vmcnt(15)
	ds_write_b128 v230, v[52:55]
	s_cbranch_vccnz .LBB0_652
	global_load_dwordx4 v[52:55], v[8:9], off

.LBB0_658:
	ds_read_b128 v[148:151], v252 offset:50176
	ds_read_b128 v[152:155], v252 offset:52224
	ds_read_b128 v[176:179], v251 offset:33792
	ds_read_b128 v[172:175], v251 offset:35840
	ds_read_b128 v[156:159], v252 offset:54272
	ds_read_b128 v[160:163], v252 offset:56320
	ds_read_b128 v[168:171], v251 offset:37888
	ds_read_b128 v[164:167], v251 offset:39936
	s_waitcnt lgkmcnt(5)
	v_mfma_f32_16x16x32_bf16 v[84:87], v[148:151], v[176:179], v[84:87]
	v_mfma_f32_16x16x32_bf16 v[88:91], v[152:155], v[176:179], v[88:91]
	s_waitcnt lgkmcnt(3)
	v_mfma_f32_16x16x32_bf16 v[92:95], v[156:159], v[176:179], v[92:95]
	s_waitcnt lgkmcnt(2)
	v_mfma_f32_16x16x32_bf16 v[96:99], v[160:163], v[176:179], v[96:99]
	s_and_b64 vcc, exec, s[38:39]
	s_waitcnt vmcnt(11)
	ds_write_b128 v230, v[64:67] offset:8192
	s_cbranch_vccnz .LBB0_660
	v_add_co_u32_e32 v12, vcc, 0x20000, v8
	s_nop 1
	v_addc_co_u32_e32 v13, vcc, 0, v9, vcc
	global_load_dwordx4 v[64:67], v[12:13], off

.LBB0_674:
	ds_read_b128 v[148:151], v252 offset:17408
	ds_read_b128 v[152:155], v252 offset:19456
	ds_read_b128 v[176:179], v251 offset:1024
	ds_read_b128 v[172:175], v251 offset:3072
	ds_read_b128 v[156:159], v252 offset:21504
	ds_read_b128 v[160:163], v252 offset:23552
	ds_read_b128 v[168:171], v251 offset:5120
	ds_read_b128 v[164:167], v251 offset:7168
	s_waitcnt lgkmcnt(5)
	v_mfma_f32_16x16x32_bf16 v[84:87], v[148:151], v[176:179], v[84:87]
	v_mfma_f32_16x16x32_bf16 v[88:91], v[152:155], v[176:179], v[88:91]
	s_waitcnt lgkmcnt(3)
	v_mfma_f32_16x16x32_bf16 v[92:95], v[156:159], v[176:179], v[92:95]
	s_waitcnt lgkmcnt(2)
	v_mfma_f32_16x16x32_bf16 v[96:99], v[160:163], v[176:179], v[96:99]
	s_and_b64 vcc, exec, s[38:39]
	s_waitcnt vmcnt(3)
	ds_write_b128 v230, v[32:35] offset:40960
	s_cbranch_vccnz .LBB0_676
	v_add_co_u32_e32 v12, vcc, 0x20000, v8
	s_nop 1
	v_addc_co_u32_e32 v13, vcc, 0, v9, vcc
	global_load_dwordx4 v[32:35], v[12:13], off offset:128

.LBB0_690:
	ds_read_b128 v[164:167], v252 offset:50176
	ds_read_b128 v[168:171], v252 offset:52224
	ds_read_b128 v[120:123], v251 offset:33792
	ds_read_b128 v[184:187], v251 offset:35840
	ds_read_b128 v[172:175], v252 offset:54272
	ds_read_b128 v[176:179], v252 offset:56320
	s_waitcnt lgkmcnt(3)
	v_mfma_f32_16x16x32_bf16 v[128:131], v[164:167], v[120:123], v[148:151]
	v_mfma_f32_16x16x32_bf16 v[124:127], v[168:171], v[120:123], v[152:155]
	s_waitcnt lgkmcnt(1)
	v_mfma_f32_16x16x32_bf16 v[116:119], v[172:175], v[120:123], v[156:159]
	s_nop 2
	ds_read_b128 v[156:159], v251 offset:37888
	ds_read_b128 v[180:183], v251 offset:39936
	s_waitcnt lgkmcnt(2)
	v_mfma_f32_16x16x32_bf16 v[120:123], v[176:179], v[120:123], v[160:163]
	s_and_b64 vcc, exec, s[38:39]
	s_cbranch_vccnz .LBB0_692
	v_add_co_u32_e32 v12, vcc, 0x20000, v8
	ds_write_b128 v230, v[64:67] offset:8192
	s_nop 0
	v_addc_co_u32_e32 v13, vcc, 0, v9, vcc
	global_load_dwordx4 v[64:67], v[12:13], off offset:256

	.amdhsa_kernel _Z14fwd_megakernel6Params
		.amdhsa_group_segment_fixed_size 65556
		.amdhsa_private_segment_fixed_size 0
		.amdhsa_kernarg_size 424
		.amdhsa_user_sgpr_count 2
		.amdhsa_user_sgpr_dispatch_ptr 0
		.amdhsa_user_sgpr_queue_ptr 0
		.amdhsa_user_sgpr_kernarg_segment_ptr 1
		.amdhsa_user_sgpr_dispatch_id 0
		.amdhsa_user_sgpr_kernarg_preload_length 0
		.amdhsa_user_sgpr_kernarg_preload_offset 0
		.amdhsa_user_sgpr_private_segment_size 0
		.amdhsa_uses_dynamic_stack 0
		.amdhsa_enable_private_segment 0
		.amdhsa_system_sgpr_workgroup_id_x 1
		.amdhsa_system_sgpr_workgroup_id_y 0
		.amdhsa_system_sgpr_workgroup_id_z 0
		.amdhsa_system_sgpr_workgroup_info 0
		.amdhsa_system_vgpr_workitem_id 2
		.amdhsa_next_free_vgpr 256
		.amdhsa_next_free_sgpr 102
		.amdhsa_accum_offset 256
		.amdhsa_reserve_vcc 1
		.amdhsa_float_round_mode_32 0
		.amdhsa_float_round_mode_16_64 0
		.amdhsa_float_denorm_mode_32 3
		.amdhsa_float_denorm_mode_16_64 3
		.amdhsa_dx10_clamp 1
		.amdhsa_ieee_mode 1
		.amdhsa_fp16_overflow 0
		.amdhsa_tg_split 0
		.amdhsa_exception_fp_ieee_invalid_op 0
		.amdhsa_exception_fp_denorm_src 0
		.amdhsa_exception_fp_ieee_div_zero 0
		.amdhsa_exception_fp_ieee_overflow 0
		.amdhsa_exception_fp_ieee_underflow 0
		.amdhsa_exception_fp_ieee_inexact 0
		.amdhsa_exception_int_div_zero 0
	.end_amdhsa_kernel

amdhsa.kernels:
  - .agpr_count:     0
    .args:
      - .offset:         0
        .size:           168
        .value_kind:     by_value
      - .offset:         168
        .size:           4
        .value_kind:     hidden_block_count_x
      - .offset:         172
        .size:           4
        .value_kind:     hidden_block_count_y
      - .offset:         176
        .size:           4
        .value_kind:     hidden_block_count_z
      - .offset:         180
        .size:           2
        .value_kind:     hidden_group_size_x
      - .offset:         182
        .size:           2
        .value_kind:     hidden_group_size_y
      - .offset:         184
        .size:           2
        .value_kind:     hidden_group_size_z
      - .offset:         186
        .size:           2
        .value_kind:     hidden_remainder_x
      - .offset:         188
        .size:           2
        .value_kind:     hidden_remainder_y
      - .offset:         190
        .size:           2
        .value_kind:     hidden_remainder_z
      - .offset:         208
        .size:           8
        .value_kind:     hidden_global_offset_x
      - .offset:         216
        .size:           8
        .value_kind:     hidden_global_offset_y
      - .offset:         224
        .size:           8
        .value_kind:     hidden_global_offset_z
      - .offset:         232
        .size:           2
        .value_kind:     hidden_grid_dims
      - .offset:         256
        .size:           8
        .value_kind:     hidden_multigrid_sync_arg
    .group_segment_fixed_size: 65556
    .kernarg_segment_align: 8
    .kernarg_segment_size: 424
    .language:       OpenCL C
    .language_version:
      - 2
      - 0
    .max_flat_workgroup_size: 256
    .name:           _Z14fwd_megakernel6Params
    .private_segment_fixed_size: 0
    .sgpr_count:     108
    .sgpr_spill_count: 165
    .symbol:         _Z14fwd_megakernel6Params.kd
    .uniform_work_group_size: 1
    .uses_dynamic_stack: false
    .vgpr_count:     256
    .vgpr_spill_count: 0
    .wavefront_size: 64
